# register prefetch across GLA-prep items: next item's codes loaded after the gate block, head skips its code loads and the store-ack wait when the token base matches
# speedup vs baseline: 1.0081x; 1.0034x over previous
; DI void gla_prep_item(const Args& A, int l, unsigned char* ldsb, int item, int tid, bool stage) {
;     ...
;     const int t = tid >> 3, dg = tid & 7;
;     const u32x4* cp = (const u32x4*)(CODES + (tok0 + t) * 32);
;     const u32x4 cq0 = cp[0], cq1 = cp[1], cq2 = cp[2], cq3 = cp[3];
;     const u32x4 qv = *(const u32x4*)(GQK + (tok0 + t) * 512 + h * 64 + 8 * dg), kv = *(const u32x4*)(GQK + (tok0 + t) * 512 + 256 + h * 64 + 8 * dg);
;     if (stage) {
;         const int idx = tid * 4, dir = idx >> 10, r = (idx >> 6) & 15, d = idx & 63;
;         const float* w = (dir ? INP(11) : INP(9)) + (size_t)l * 16 * 256 + r * 256 + h * 64 + d;
;         *(f32x4*)(wg + idx) = *(const f32x4*)w;
;         if (tid < 128) { const int dr = tid >> 6, dd = tid & 63; bg[tid] = (dr ? INP(12) : INP(10))[l * 256 + h * 64 + dd]; }
;         __syncthreads();
;     }
;     {
;         float cf[32];
; #pragma unroll
;         for (int j = 0; j < 4; ++j) { const u32x4 v = j == 0 ? cq0 : (j == 1 ? cq1 : (j == 2 ? cq2 : cq3)); cf[8 * j + 0] = bflo(v.x); cf[8 * j + 1] = bfhi(v.x); cf[8 * j + 2] = bflo(v.y); cf[8 * j + 3] = bfhi(v.y); cf[8 * j + 4] = bflo(v.z); cf[8 * j + 5] = bfhi(v.z); cf[8 * j + 6] = bflo(v.w); cf[8 * j + 7] = bfhi(v.w); }
; #pragma unroll
;         for (int dir = 0; dir < 2; ++dir) {
;             float z[8];
; #pragma unroll
;             for (int dd = 0; dd < 8; ++dd) z[dd] = bg[dir * 64 + 8 * dg + dd];
; #pragma unroll
;             for (int r = 0; r < 16; ++r) {
;                 const f32x4 w0 = *(const f32x4*)(wg + dir * 1024 + r * 64 + 8 * dg), w1 = *(const f32x4*)(wg + dir * 1024 + r * 64 + 8 * dg + 4);
;                 const float cv = cf[dir * 16 + r];
;                 z[0] += cv * w0[0]; z[1] += cv * w0[1]; z[2] += cv * w0[2]; z[3] += cv * w0[3]; z[4] += cv * w1[0]; z[5] += cv * w1[1]; z[6] += cv * w1[2]; z[7] += cv * w1[3];
;             }
; #pragma unroll
;             for (int dd = 0; dd < 8; ++dd) gl[(dir * 64 + t) * 65 + 8 * dg + dd] = log_sigmoid_f(z[dd]) * (1.0f / 16.0f);
;         }
;     }
;     __syncthreads();
;     {
;         const int dir = tid >> 8, seg = (tid >> 6) & 3, d = tid & 63;
;         float* gp = gl + (dir * 64 + 16 * seg) * 65 + d; float v[16];
; #pragma unroll
;         for (int tt = 0; tt < 16; ++tt) v[tt] = gp[tt * 65];
;         if (dir == 0) {
; #pragma unroll
;             for (int tt = 1; tt < 16; ++tt) v[tt] += v[tt - 1];
.LBB0_557:
	v_readlane_b32 s2, v245, 1
	v_readlane_b32 s3, v245, 2
	v_mov_b32_e32 v0, v165
	s_and_b64 vcc, exec, s[2:3]
	s_cbranch_vccz .LBB0_592
	s_movk_i32 s2, 0xff
	v_and_b32_e32 v6, 63, v0
	v_ashrrev_i32_e32 v7, 6, v0
	v_lshrrev_b32_e32 v9, 2, v0
	v_cmp_lt_u32_e64 s[42:43], s2, v0
	s_movk_i32 s2, 0x80
	v_and_b32_e32 v8, 3, v7
	v_and_b32_e32 v9, 0x3fffffc0, v9
	v_lshlrev_b32_e32 v10, 2, v6
	v_ashrrev_i32_e32 v26, 3, v0
	v_lshlrev_b32_e32 v2, 3, v0
	v_cmp_gt_i32_e64 s[44:45], s2, v0
	v_lshl_or_b32 v31, s68, 8, v6
	s_movk_i32 s2, 0x104
	v_lshl_or_b32 v9, v8, 4, v9
	v_add_u32_e32 v30, 0, v10
	v_and_b32_e32 v28, 56, v2
	v_mul_lo_u32 v5, v26, s2
	v_mad_u64_u32 v[32:33], s[2:3], v9, s2, v[30:31]
	v_and_b32_e32 v9, 0x3fffff00, v0
	v_lshlrev_b32_e32 v3, 4, v0
	v_lshl_add_u32 v35, v28, 2, 0
	v_lshl_add_u32 v9, v9, 2, 0
	v_lshlrev_b32_e32 v11, 8, v8
	v_lshlrev_b32_e32 v2, 2, v0
	v_and_b32_e32 v4, 0xf00, v3
	v_add_u32_e32 v29, 0, v3
	v_cmp_lt_u32_e64 s[46:47], 63, v0
	v_mul_lo_u32 v3, v0, -12
	v_add3_u32 v33, v9, v11, v10
	v_add_u32_e32 v37, v35, v5
	v_mul_u32_u24_e32 v5, 0x48, v28
	v_cmp_gt_u32_e32 vcc, 64, v0
	v_bfe_u32 v34, v0, 3, 6
	v_and_b32_e32 v36, 7, v0
	v_ashrrev_i32_e32 v10, 9, v0
	v_add_u32_e32 v0, 0x200, v0
	v_cmp_eq_u32_e64 s[48:49], 0, v8
	v_cmp_ne_u32_e64 s[50:51], 0, v8
	v_cmp_gt_u32_e64 s[52:53], 2, v8
	v_cmp_eq_u32_e64 s[54:55], 3, v8
	v_cmp_ne_u32_e64 s[56:57], 3, v8
	v_cmp_lt_u32_e64 s[58:59], 1, v8
	v_lshlrev_b32_e32 v8, 1, v26
	v_lshlrev_b32_e32 v5, 1, v5
	v_ashrrev_i32_e32 v0, 9, v0
	v_add3_u32 v64, 0, v8, v5
	v_add_u32_e32 v5, 0, v5
	v_lshl_or_b32 v11, v10, 6, v34
	s_movk_i32 s2, 0x90
	v_lshlrev_b32_e32 v38, 8, v10
	v_lshl_or_b32 v10, v0, 6, v34
	v_and_b32_e32 v2, 60, v2
	v_add_u32_e32 v65, v5, v8
	v_mul_i32_i24_e32 v8, 0xffffff74, v28
	v_cndmask_b32_e32 v9, v196, v197, vcc
	v_lshlrev_b32_e32 v74, 5, v7
	v_lshl_add_u32 v7, v36, 4, 0
	v_mul_lo_u32 v11, v11, s2
	v_mul_lo_u32 v10, v10, s2
	v_lshlrev_b32_e32 v40, 8, v0
	s_lshl_b32 s38, s68, 12
	s_mov_b32 s39, s9
	v_ashrrev_i32_e32 v27, 31, v26
	v_add_u32_e32 v66, 0x90, v65
	v_add_u32_e32 v67, 0x120, v65
	v_add_u32_e32 v68, 0x1b0, v65
	v_add_u32_e32 v69, 0x240, v65
	v_add_u32_e32 v70, 0x2d0, v65
	v_add_u32_e32 v71, 0x360, v65
	v_add_u32_e32 v72, 0x3f0, v64
	v_add_u32_e32 v73, 0x3f0, v65
	v_ashrrev_i32_e32 v39, 31, v38
	v_ashrrev_i32_e32 v41, 31, v40
	s_mov_b32 s29, -1
	v_lshlrev_b32_e32 v42, 2, v4
	v_lshlrev_b32_e32 v44, 2, v2
	v_add_u32_e32 v75, v29, v3
	v_add_u32_e32 v76, v5, v8
	v_add_u32_e32 v77, v30, v9
	v_lshlrev_b32_e32 v46, 2, v6
	v_add_u32_e32 v78, v7, v11
	v_add_u32_e32 v79, v7, v10
	v_readlane_b32 s10, v244, 6
	s_mov_b32 s99, 0x7fffffff
	s_branch .LBB0_560

; DI void gla_prep_item(const Args& A, int l, unsigned char* ldsb, int item, int tid, bool stage) {
;     ...
;     const bf16* CODES = (const bf16*)(R + R_CODES); const bf16* GQK = (const bf16*)(R + R_GQK);
;     bf16* GP = (bf16*)(R + R_GP); bf16* KT = (bf16*)(R + R_KT); float* DEC = (float*)(R + R_DEC);
;     const int c = item & 63, bh = item >> 6, h = bh & 3, b = bh >> 2;
;     const size_t tok0 = (size_t)b * SEQ + c * 64;
;     const int t = tid >> 3, dg = tid & 7;
;     const u32x4* cp = (const u32x4*)(CODES + (tok0 + t) * 32);
;     const u32x4 cq0 = cp[0], cq1 = cp[1], cq2 = cp[2], cq3 = cp[3];
;     const u32x4 qv = *(const u32x4*)(GQK + (tok0 + t) * 512 + h * 64 + 8 * dg), kv = *(const u32x4*)(GQK + (tok0 + t) * 512 + 256 + h * 64 + 8 * dg);
.LBB0_560:
	v_readlane_b32 s2, v244, 3
	s_add_i32 s2, s2, s10
	s_ashr_i32 s2, s2, 2
	s_and_b32 s2, s2, -8
	v_readlane_b32 s3, v245, 3
	s_or_b32 s8, s3, s2
	v_readlane_b32 s2, v245, 4
	v_readlane_b32 s3, v245, 5
	s_and_b64 s[2:3], s[2:3], exec
	s_cselect_b32 s2, s8, s10
	v_readlane_b32 s3, v246, 62
	s_or_b32 s8, s2, s3
	s_and_b64 s[2:3], s[6:7], exec
	s_cselect_b32 s31, s8, s10
	s_movk_i32 s2, 0xa8
	s_mov_b32 s14, s29
	s_bfe_u32 s29, s31, 0x20006
	s_ashr_i32 s3, s2, 31
	s_add_u32 s2, s0, s2
	s_addc_u32 s3, s1, s3
	s_ashr_i32 s12, s31, 8
	s_ashr_i32 s13, s12, 31
	s_lshl_b32 s8, s31, 6
	s_load_dwordx2 s[62:63], s[2:3], 0x0
	s_lshl_b64 s[60:61], s[12:13], 12
	s_and_b32 s40, s8, 0xfc0
	s_or_b32 s60, s60, s40
	v_lshl_add_u64 v[48:49], s[60:61], 0, v[26:27]
	v_lshlrev_b64 v[2:3], 6, v[48:49]
	s_waitcnt lgkmcnt(0)
	v_lshl_add_u64 v[2:3], s[62:63], 0, v[2:3]
	s_mov_b64 s[2:3], 0x1f600000
	v_lshl_add_u64 v[4:5], v[2:3], 0, s[2:3]
	s_mov_b32 s2, 0x1f600000
	v_add_co_u32_e32 v2, vcc, s2, v2
	s_and_b32 s30, s31, 0xc0
	s_nop 0
	v_addc_co_u32_e32 v3, vcc, 0, v3, vcc
	s_bitset0_b32 s99, 31
	s_cmp_eq_u32 s60, s99
	s_cselect_b32 s99, 0x80000000, 0
	s_or_b32 s99, s99, s60
	s_add_i32 s99, s99, 0x200
	s_bitcmp1_b32 s99, 31
	s_cbranch_scc1 .Lpp_skip
	global_load_dwordx4 v[22:25], v[2:3], off
	global_load_dwordx4 v[10:13], v[4:5], off offset:48
	global_load_dwordx4 v[14:17], v[4:5], off offset:32
	global_load_dwordx4 v[18:21], v[4:5], off offset:16
.Lpp_skip:
	v_add_co_u32_e32 v90, vcc, 0x8000, v4
	s_nop 1
	v_addc_co_u32_e32 v91, vcc, 0, v5, vcc
	v_lshlrev_b64 v[2:3], 10, v[48:49]
	s_lshl_b32 s8, s30, 1
	v_lshl_add_u64 v[2:3], s[62:63], 0, v[2:3]
	v_lshl_add_u64 v[2:3], v[2:3], 0, s[8:9]
	v_lshlrev_b32_e32 v0, 1, v28
	v_lshl_add_u64 v[2:3], v[2:3], 0, v[0:1]
	s_mov_b64 s[2:3], 0x1b600000
	v_lshl_add_u64 v[4:5], v[2:3], 0, s[2:3]
	v_add_co_u32_e32 v2, vcc, 0x1b600000, v2
	s_cmp_eq_u32 s29, s14
	s_nop 0
	v_addc_co_u32_e32 v3, vcc, 0, v3, vcc
	v_add_co_u32_e32 v92, vcc, 0x80000, v4
	s_nop 1
	v_addc_co_u32_e32 v93, vcc, 0, v5, vcc
	global_load_dwordx4 v[6:9], v[2:3], off
	s_nop 0
	global_load_dwordx4 v[2:5], v[4:5], off offset:512
	global_load_dword v88, v[90:91], off
	global_load_dword v88, v[92:93], off
	global_load_dword v88, v[92:93], off offset:512
	s_cbranch_scc1 .LBB0_572
	s_and_saveexec_b64 s[2:3], s[42:43]
	s_xor_b64 s[2:3], exec, s[2:3]
	s_cbranch_execz .LBB0_563
	s_movk_i32 s8, 0x58

; DI float bflo(unsigned w) { return __uint_as_float(w << 16); }
; DI float bfhi(unsigned w) { return __uint_as_float(w & 0xffff0000u); }
; #define INP(i) ((const float*)karg(8 * (i)))
; DI void gla_prep_item(const Args& A, int l, unsigned char* ldsb, int item, int tid, bool stage) {
;     ...
;     const u32x4* cp = (const u32x4*)(CODES + (tok0 + t) * 32);
;     const u32x4 cq0 = cp[0], cq1 = cp[1], cq2 = cp[2], cq3 = cp[3];
;     const u32x4 qv = *(const u32x4*)(GQK + (tok0 + t) * 512 + h * 64 + 8 * dg), kv = *(const u32x4*)(GQK + (tok0 + t) * 512 + 256 + h * 64 + 8 * dg);
;     if (stage) {
;         const int idx = tid * 4, dir = idx >> 10, r = (idx >> 6) & 15, d = idx & 63;
;         const float* w = (dir ? INP(11) : INP(9)) + (size_t)l * 16 * 256 + r * 256 + h * 64 + d;
;         *(f32x4*)(wg + idx) = *(const f32x4*)w;
;         if (tid < 128) { const int dr = tid >> 6, dd = tid & 63; bg[tid] = (dr ? INP(12) : INP(10))[l * 256 + h * 64 + dd]; }
;         __syncthreads();
;     }
;     {
;         float cf[32];
; #pragma unroll
;         for (int j = 0; j < 4; ++j) { const u32x4 v = j == 0 ? cq0 : (j == 1 ? cq1 : (j == 2 ? cq2 : cq3)); cf[8 * j + 0] = bflo(v.x); cf[8 * j + 1] = bfhi(v.x); cf[8 * j + 2] = bflo(v.y); cf[8 * j + 3] = bfhi(v.y); cf[8 * j + 4] = bflo(v.z); cf[8 * j + 5] = bfhi(v.z); cf[8 * j + 6] = bflo(v.w); cf[8 * j + 7] = bfhi(v.w); }
; #pragma unroll
;         for (int dir = 0; dir < 2; ++dir) {
;             float z[8];
; #pragma unroll
;             for (int dd = 0; dd < 8; ++dd) z[dd] = bg[dir * 64 + 8 * dg + dd];
; #pragma unroll
;             for (int r = 0; r < 16; ++r) {
;                 const f32x4 w0 = *(const f32x4*)(wg + dir * 1024 + r * 64 + 8 * dg), w1 = *(const f32x4*)(wg + dir * 1024 + r * 64 + 8 * dg + 4);
;                 const float cv = cf[dir * 16 + r];
;                 z[0] += cv * w0[0]; z[1] += cv * w0[1]; z[2] += cv * w0[2]; z[3] += cv * w0[3]; z[4] += cv * w1[0]; z[5] += cv * w1[1]; z[6] += cv * w1[2]; z[7] += cv * w1[3];
;             }
.LBB0_572:
	s_bitcmp1_b32 s99, 31
	s_cbranch_scc1 .Lpp_use
	s_waitcnt vmcnt(5)
	s_branch .Lpp_go
.Lpp_use:
	s_waitcnt vmcnt(9)
	v_mov_b32_e32 v22, v118
	v_mov_b32_e32 v23, v119
	v_mov_b32_e32 v24, v120
	v_mov_b32_e32 v25, v121
	v_mov_b32_e32 v10, v122
	v_mov_b32_e32 v11, v123
	v_mov_b32_e32 v12, v124
	v_mov_b32_e32 v13, v125
	v_mov_b32_e32 v14, v126
	v_mov_b32_e32 v15, v127
	v_mov_b32_e32 v16, v128
	v_mov_b32_e32 v17, v129
	v_mov_b32_e32 v18, v130
	v_mov_b32_e32 v19, v131
	v_mov_b32_e32 v20, v132
	v_mov_b32_e32 v21, v133
.Lpp_go:
	ds_read_b128 v[94:97], v35 offset:43520
	ds_read_b128 v[98:101], v35 offset:43536
	ds_read_b128 v[118:121], v35 offset:35328
	ds_read_b128 v[122:125], v35 offset:35344
	ds_read_b128 v[126:129], v35 offset:35584
	ds_read_b128 v[130:133], v35 offset:35600
	ds_read_b128 v[134:137], v35 offset:35840
	ds_read_b128 v[138:141], v35 offset:35856
	ds_read_b128 v[142:145], v35 offset:36096
	ds_read_b128 v[146:149], v35 offset:36112
	v_lshlrev_b32_e32 v102, 16, v22
	v_and_b32_e32 v103, 0xffff0000, v22
	v_lshlrev_b32_e32 v104, 16, v23
	v_and_b32_e32 v105, 0xffff0000, v23
	v_lshlrev_b32_e32 v106, 16, v24
	v_and_b32_e32 v107, 0xffff0000, v24
	v_lshlrev_b32_e32 v108, 16, v25
	v_and_b32_e32 v109, 0xffff0000, v25
	v_lshlrev_b32_e32 v110, 16, v18
	v_and_b32_e32 v111, 0xffff0000, v18
	v_lshlrev_b32_e32 v112, 16, v19
	v_and_b32_e32 v113, 0xffff0000, v19
	v_lshlrev_b32_e32 v114, 16, v20
	v_and_b32_e32 v115, 0xffff0000, v20
	v_lshlrev_b32_e32 v116, 16, v21
	v_and_b32_e32 v117, 0xffff0000, v21
	s_waitcnt lgkmcnt(6)
	v_fmac_f32_e32 v94, v118, v102
	v_fmac_f32_e32 v95, v119, v102
	v_fmac_f32_e32 v96, v120, v102
	v_fmac_f32_e32 v97, v121, v102
	v_fmac_f32_e32 v98, v122, v102
	v_fmac_f32_e32 v99, v123, v102
	v_fmac_f32_e32 v100, v124, v102
	v_fmac_f32_e32 v101, v125, v102
	ds_read_b128 v[118:121], v35 offset:36352
	ds_read_b128 v[122:125], v35 offset:36368
	s_waitcnt lgkmcnt(6)
	v_fmac_f32_e32 v94, v126, v103
	v_fmac_f32_e32 v95, v127, v103
	v_fmac_f32_e32 v96, v128, v103
	v_fmac_f32_e32 v97, v129, v103
	v_fmac_f32_e32 v98, v130, v103
	v_fmac_f32_e32 v99, v131, v103
	v_fmac_f32_e32 v100, v132, v103
	v_fmac_f32_e32 v101, v133, v103
	ds_read_b128 v[126:129], v35 offset:36608
	ds_read_b128 v[130:133], v35 offset:36624
	s_waitcnt lgkmcnt(6)
	v_fmac_f32_e32 v94, v134, v104
	v_fmac_f32_e32 v95, v135, v104
	v_fmac_f32_e32 v96, v136, v104
	v_fmac_f32_e32 v97, v137, v104
	v_fmac_f32_e32 v98, v138, v104
	v_fmac_f32_e32 v99, v139, v104
	v_fmac_f32_e32 v100, v140, v104
	v_fmac_f32_e32 v101, v141, v104
	ds_read_b128 v[134:137], v35 offset:36864
	ds_read_b128 v[138:141], v35 offset:36880
	s_waitcnt lgkmcnt(6)
	v_fmac_f32_e32 v94, v142, v105
	v_fmac_f32_e32 v95, v143, v105
	v_fmac_f32_e32 v96, v144, v105
	v_fmac_f32_e32 v97, v145, v105
	v_fmac_f32_e32 v98, v146, v105
	v_fmac_f32_e32 v99, v147, v105
	v_fmac_f32_e32 v100, v148, v105
	v_fmac_f32_e32 v101, v149, v105
	ds_read_b128 v[142:145], v35 offset:37120
	ds_read_b128 v[146:149], v35 offset:37136
	s_waitcnt lgkmcnt(6)
	v_fmac_f32_e32 v94, v118, v106
	v_fmac_f32_e32 v95, v119, v106
	v_fmac_f32_e32 v96, v120, v106
	v_fmac_f32_e32 v97, v121, v106
	v_fmac_f32_e32 v98, v122, v106
	v_fmac_f32_e32 v99, v123, v106
	v_fmac_f32_e32 v100, v124, v106
	v_fmac_f32_e32 v101, v125, v106
	ds_read_b128 v[118:121], v35 offset:37376
	ds_read_b128 v[122:125], v35 offset:37392
	s_waitcnt lgkmcnt(6)
	v_fmac_f32_e32 v94, v126, v107
	v_fmac_f32_e32 v95, v127, v107
	v_fmac_f32_e32 v96, v128, v107
	v_fmac_f32_e32 v97, v129, v107
	v_fmac_f32_e32 v98, v130, v107
	v_fmac_f32_e32 v99, v131, v107
	v_fmac_f32_e32 v100, v132, v107
	v_fmac_f32_e32 v101, v133, v107
	ds_read_b128 v[126:129], v35 offset:37632
	ds_read_b128 v[130:133], v35 offset:37648
	s_waitcnt lgkmcnt(6)
	v_fmac_f32_e32 v94, v134, v108
	v_fmac_f32_e32 v95, v135, v108
	v_fmac_f32_e32 v96, v136, v108
	v_fmac_f32_e32 v97, v137, v108
	v_fmac_f32_e32 v98, v138, v108
	v_fmac_f32_e32 v99, v139, v108
	v_fmac_f32_e32 v100, v140, v108
	v_fmac_f32_e32 v101, v141, v108
	ds_read_b128 v[134:137], v35 offset:37888
	ds_read_b128 v[138:141], v35 offset:37904
	s_waitcnt lgkmcnt(6)
	v_fmac_f32_e32 v94, v142, v109
	v_fmac_f32_e32 v95, v143, v109
	v_fmac_f32_e32 v96, v144, v109
	v_fmac_f32_e32 v97, v145, v109
	v_fmac_f32_e32 v98, v146, v109
	v_fmac_f32_e32 v99, v147, v109
	v_fmac_f32_e32 v100, v148, v109
	v_fmac_f32_e32 v101, v149, v109
	ds_read_b128 v[142:145], v35 offset:38144
	ds_read_b128 v[146:149], v35 offset:38160
	s_waitcnt lgkmcnt(6)
	v_fmac_f32_e32 v94, v118, v110
	v_fmac_f32_e32 v95, v119, v110
	v_fmac_f32_e32 v96, v120, v110
	v_fmac_f32_e32 v97, v121, v110
	v_fmac_f32_e32 v98, v122, v110
	v_fmac_f32_e32 v99, v123, v110
	v_fmac_f32_e32 v100, v124, v110
	v_fmac_f32_e32 v101, v125, v110
	ds_read_b128 v[118:121], v35 offset:38400
	ds_read_b128 v[122:125], v35 offset:38416
	s_waitcnt lgkmcnt(6)
	v_fmac_f32_e32 v94, v126, v111
	v_fmac_f32_e32 v95, v127, v111
	v_fmac_f32_e32 v96, v128, v111
	v_fmac_f32_e32 v97, v129, v111
	v_fmac_f32_e32 v98, v130, v111
	v_fmac_f32_e32 v99, v131, v111
	v_fmac_f32_e32 v100, v132, v111
	v_fmac_f32_e32 v101, v133, v111
	ds_read_b128 v[126:129], v35 offset:38656
	ds_read_b128 v[130:133], v35 offset:38672
	s_waitcnt lgkmcnt(6)
	v_fmac_f32_e32 v94, v134, v112
	v_fmac_f32_e32 v95, v135, v112
	v_fmac_f32_e32 v96, v136, v112
	v_fmac_f32_e32 v97, v137, v112
	v_fmac_f32_e32 v98, v138, v112
	v_fmac_f32_e32 v99, v139, v112
	v_fmac_f32_e32 v100, v140, v112
	v_fmac_f32_e32 v101, v141, v112
	ds_read_b128 v[134:137], v35 offset:38912
	ds_read_b128 v[138:141], v35 offset:38928
	s_waitcnt lgkmcnt(6)
; DI float log_sigmoid_f(float z) { return fminf(z, 0.f) - __logf(1.0f + __expf(-fabsf(z))); }
; DI void gla_prep_item(const Args& A, int l, unsigned char* ldsb, int item, int tid, bool stage) {
;     ...
;             float z[8];
; #pragma unroll
;             for (int dd = 0; dd < 8; ++dd) z[dd] = bg[dir * 64 + 8 * dg + dd];
; #pragma unroll
;             for (int r = 0; r < 16; ++r) {
;                 const f32x4 w0 = *(const f32x4*)(wg + dir * 1024 + r * 64 + 8 * dg), w1 = *(const f32x4*)(wg + dir * 1024 + r * 64 + 8 * dg + 4);
;                 const float cv = cf[dir * 16 + r];
;                 z[0] += cv * w0[0]; z[1] += cv * w0[1]; z[2] += cv * w0[2]; z[3] += cv * w0[3]; z[4] += cv * w1[0]; z[5] += cv * w1[1]; z[6] += cv * w1[2]; z[7] += cv * w1[3];
;             }
; #pragma unroll
;             for (int dd = 0; dd < 8; ++dd) gl[(dir * 64 + t) * 65 + 8 * dg + dd] = log_sigmoid_f(z[dd]) * (1.0f / 16.0f);
	v_fmac_f32_e32 v94, v142, v113
	v_fmac_f32_e32 v95, v143, v113
	v_fmac_f32_e32 v96, v144, v113
	v_fmac_f32_e32 v97, v145, v113
	v_fmac_f32_e32 v98, v146, v113
	v_fmac_f32_e32 v99, v147, v113
	v_fmac_f32_e32 v100, v148, v113
	v_fmac_f32_e32 v101, v149, v113
	ds_read_b128 v[142:145], v35 offset:39168
	ds_read_b128 v[146:149], v35 offset:39184
	s_waitcnt lgkmcnt(6)
	v_fmac_f32_e32 v94, v118, v114
	v_fmac_f32_e32 v95, v119, v114
	v_fmac_f32_e32 v96, v120, v114
	v_fmac_f32_e32 v97, v121, v114
	v_fmac_f32_e32 v98, v122, v114
	v_fmac_f32_e32 v99, v123, v114
	v_fmac_f32_e32 v100, v124, v114
	v_fmac_f32_e32 v101, v125, v114
	s_waitcnt lgkmcnt(4)
	v_fmac_f32_e32 v94, v126, v115
	v_fmac_f32_e32 v95, v127, v115
	v_fmac_f32_e32 v96, v128, v115
	v_fmac_f32_e32 v97, v129, v115
	v_fmac_f32_e32 v98, v130, v115
	v_fmac_f32_e32 v99, v131, v115
	v_fmac_f32_e32 v100, v132, v115
	v_fmac_f32_e32 v101, v133, v115
	s_waitcnt lgkmcnt(2)
	v_fmac_f32_e32 v94, v134, v116
	v_fmac_f32_e32 v95, v135, v116
	v_fmac_f32_e32 v96, v136, v116
	v_fmac_f32_e32 v97, v137, v116
	v_fmac_f32_e32 v98, v138, v116
	v_fmac_f32_e32 v99, v139, v116
	v_fmac_f32_e32 v100, v140, v116
	v_fmac_f32_e32 v101, v141, v116
	s_waitcnt lgkmcnt(0)
	v_fmac_f32_e32 v94, v142, v117
	v_fmac_f32_e32 v95, v143, v117
	v_fmac_f32_e32 v96, v144, v117
	v_fmac_f32_e32 v97, v145, v117
	v_fmac_f32_e32 v98, v146, v117
	v_fmac_f32_e32 v99, v147, v117
	v_fmac_f32_e32 v100, v148, v117
	v_fmac_f32_e32 v101, v149, v117
	v_mul_f32_e64 v118, |v94|, s11
	v_mul_f32_e64 v119, |v95|, s11
	v_mul_f32_e64 v120, |v96|, s11
	v_mul_f32_e64 v121, |v97|, s11
	v_mul_f32_e64 v122, |v98|, s11
	v_mul_f32_e64 v123, |v99|, s11
	v_mul_f32_e64 v124, |v100|, s11
	v_mul_f32_e64 v125, |v101|, s11
	v_exp_f32_e32 v118, v118
	v_exp_f32_e32 v119, v119
	v_exp_f32_e32 v120, v120
	v_exp_f32_e32 v121, v121
	v_exp_f32_e32 v122, v122
	v_exp_f32_e32 v123, v123
	v_exp_f32_e32 v124, v124
	v_exp_f32_e32 v125, v125
	v_min_f32_e32 v142, 0, v94
	v_min_f32_e32 v143, 0, v95
	v_min_f32_e32 v144, 0, v96
	v_min_f32_e32 v145, 0, v97
	v_min_f32_e32 v146, 0, v98
	v_min_f32_e32 v147, 0, v99
	v_min_f32_e32 v148, 0, v100
	v_min_f32_e32 v149, 0, v101
	v_add_f32_e32 v118, 1.0, v118
	v_add_f32_e32 v119, 1.0, v119
	v_add_f32_e32 v120, 1.0, v120
	v_add_f32_e32 v121, 1.0, v121
	v_add_f32_e32 v122, 1.0, v122
	v_add_f32_e32 v123, 1.0, v123
	v_add_f32_e32 v124, 1.0, v124
	v_add_f32_e32 v125, 1.0, v125
	v_log_f32_e32 v126, v118
	v_log_f32_e32 v127, v119
	v_log_f32_e32 v128, v120
	v_log_f32_e32 v129, v121
	v_log_f32_e32 v130, v122
	v_log_f32_e32 v131, v123
	v_log_f32_e32 v132, v124
	v_log_f32_e32 v133, v125
	s_nop 0
	v_mul_f32_e32 v134, 0x3f317217, v126
	v_mul_f32_e32 v135, 0x3f317217, v127
	v_mul_f32_e32 v136, 0x3f317217, v128
	v_mul_f32_e32 v137, 0x3f317217, v129
	v_mul_f32_e32 v138, 0x3f317217, v130
	v_mul_f32_e32 v139, 0x3f317217, v131
	v_mul_f32_e32 v140, 0x3f317217, v132
	v_mul_f32_e32 v141, 0x3f317217, v133
	v_fma_f32 v134, v126, s81, -v134
	v_fma_f32 v135, v127, s81, -v135
	v_fma_f32 v136, v128, s81, -v136
	v_fma_f32 v137, v129, s81, -v137
	v_fma_f32 v138, v130, s81, -v138
	v_fma_f32 v139, v131, s81, -v139
	v_fma_f32 v140, v132, s81, -v140
	v_fma_f32 v141, v133, s81, -v141
	v_fmac_f32_e32 v134, 0x3377d1cf, v126
	v_fmac_f32_e32 v135, 0x3377d1cf, v127
	v_fmac_f32_e32 v136, 0x3377d1cf, v128
	v_fmac_f32_e32 v137, 0x3377d1cf, v129
	v_fmac_f32_e32 v138, 0x3377d1cf, v130
	v_fmac_f32_e32 v139, 0x3377d1cf, v131
	v_fmac_f32_e32 v140, 0x3377d1cf, v132
	v_fmac_f32_e32 v141, 0x3377d1cf, v133
	v_fmac_f32_e32 v134, 0x3f317217, v126
	v_fmac_f32_e32 v135, 0x3f317217, v127
	v_fmac_f32_e32 v136, 0x3f317217, v128
	v_fmac_f32_e32 v137, 0x3f317217, v129
	v_fmac_f32_e32 v138, 0x3f317217, v130
	v_fmac_f32_e32 v139, 0x3f317217, v131
	v_fmac_f32_e32 v140, 0x3f317217, v132
	v_fmac_f32_e32 v141, 0x3f317217, v133
	v_sub_f32_e32 v142, v142, v134
	v_sub_f32_e32 v143, v143, v135
	v_sub_f32_e32 v144, v144, v136
	v_sub_f32_e32 v145, v145, v137
	v_sub_f32_e32 v146, v146, v138
	v_sub_f32_e32 v147, v147, v139
	v_sub_f32_e32 v148, v148, v140
	v_sub_f32_e32 v149, v149, v141
	v_mul_f32_e32 v142, s18, v142
	v_mul_f32_e32 v143, s18, v143
	v_mul_f32_e32 v144, s18, v144
	v_mul_f32_e32 v145, s18, v145
	v_mul_f32_e32 v146, s18, v146
	v_mul_f32_e32 v147, s18, v147
	v_mul_f32_e32 v148, s18, v148
	v_mul_f32_e32 v149, s18, v149
	ds_write2_b32 v37, v142, v143 offset0:0 offset1:1
	ds_write2_b32 v37, v144, v145 offset0:2 offset1:3
	ds_write2_b32 v37, v146, v147 offset0:4 offset1:5
	ds_write2_b32 v37, v148, v149 offset0:6 offset1:7
	ds_read_b128 v[94:97], v35 offset:43776
	ds_read_b128 v[98:101], v35 offset:43792
	ds_read_b128 v[118:121], v35 offset:39424
	ds_read_b128 v[122:125], v35 offset:39440
	ds_read_b128 v[126:129], v35 offset:39680
	ds_read_b128 v[130:133], v35 offset:39696
	ds_read_b128 v[134:137], v35 offset:39936
	ds_read_b128 v[138:141], v35 offset:39952
	ds_read_b128 v[142:145], v35 offset:40192
	ds_read_b128 v[146:149], v35 offset:40208
	v_lshlrev_b32_e32 v102, 16, v14
	v_and_b32_e32 v103, 0xffff0000, v14
	v_lshlrev_b32_e32 v104, 16, v15
	v_and_b32_e32 v105, 0xffff0000, v15
	v_lshlrev_b32_e32 v106, 16, v16
	v_and_b32_e32 v107, 0xffff0000, v16
	v_lshlrev_b32_e32 v108, 16, v17
	v_and_b32_e32 v109, 0xffff0000, v17
	v_lshlrev_b32_e32 v110, 16, v10
	v_and_b32_e32 v111, 0xffff0000, v10
	v_lshlrev_b32_e32 v112, 16, v11
	v_and_b32_e32 v113, 0xffff0000, v11
	v_lshlrev_b32_e32 v114, 16, v12
	v_and_b32_e32 v115, 0xffff0000, v12
	v_lshlrev_b32_e32 v116, 16, v13
	v_and_b32_e32 v117, 0xffff0000, v13
	s_waitcnt lgkmcnt(6)
; DI void gla_prep_item(const Args& A, int l, unsigned char* ldsb, int item, int tid, bool stage) {
;     ...
;             for (int r = 0; r < 16; ++r) {
;                 const f32x4 w0 = *(const f32x4*)(wg + dir * 1024 + r * 64 + 8 * dg), w1 = *(const f32x4*)(wg + dir * 1024 + r * 64 + 8 * dg + 4);
;                 const float cv = cf[dir * 16 + r];
;                 z[0] += cv * w0[0]; z[1] += cv * w0[1]; z[2] += cv * w0[2]; z[3] += cv * w0[3]; z[4] += cv * w1[0]; z[5] += cv * w1[1]; z[6] += cv * w1[2]; z[7] += cv * w1[3];
;             }
	v_fmac_f32_e32 v94, v118, v102
	v_fmac_f32_e32 v95, v119, v102
	v_fmac_f32_e32 v96, v120, v102
	v_fmac_f32_e32 v97, v121, v102
	v_fmac_f32_e32 v98, v122, v102
	v_fmac_f32_e32 v99, v123, v102
	v_fmac_f32_e32 v100, v124, v102
	v_fmac_f32_e32 v101, v125, v102
	ds_read_b128 v[118:121], v35 offset:40448
	ds_read_b128 v[122:125], v35 offset:40464
	s_waitcnt lgkmcnt(6)
	v_fmac_f32_e32 v94, v126, v103
	v_fmac_f32_e32 v95, v127, v103
	v_fmac_f32_e32 v96, v128, v103
	v_fmac_f32_e32 v97, v129, v103
	v_fmac_f32_e32 v98, v130, v103
	v_fmac_f32_e32 v99, v131, v103
	v_fmac_f32_e32 v100, v132, v103
	v_fmac_f32_e32 v101, v133, v103
	ds_read_b128 v[126:129], v35 offset:40704
	ds_read_b128 v[130:133], v35 offset:40720
	s_waitcnt lgkmcnt(6)
	v_fmac_f32_e32 v94, v134, v104
	v_fmac_f32_e32 v95, v135, v104
	v_fmac_f32_e32 v96, v136, v104
	v_fmac_f32_e32 v97, v137, v104
	v_fmac_f32_e32 v98, v138, v104
	v_fmac_f32_e32 v99, v139, v104
	v_fmac_f32_e32 v100, v140, v104
	v_fmac_f32_e32 v101, v141, v104
	ds_read_b128 v[134:137], v35 offset:40960
	ds_read_b128 v[138:141], v35 offset:40976
	s_waitcnt lgkmcnt(6)
	v_fmac_f32_e32 v94, v142, v105
	v_fmac_f32_e32 v95, v143, v105
	v_fmac_f32_e32 v96, v144, v105
	v_fmac_f32_e32 v97, v145, v105
	v_fmac_f32_e32 v98, v146, v105
	v_fmac_f32_e32 v99, v147, v105
	v_fmac_f32_e32 v100, v148, v105
	v_fmac_f32_e32 v101, v149, v105
	ds_read_b128 v[142:145], v35 offset:41216
	ds_read_b128 v[146:149], v35 offset:41232
	s_waitcnt lgkmcnt(6)
	v_fmac_f32_e32 v94, v118, v106
	v_fmac_f32_e32 v95, v119, v106
	v_fmac_f32_e32 v96, v120, v106
	v_fmac_f32_e32 v97, v121, v106
	v_fmac_f32_e32 v98, v122, v106
	v_fmac_f32_e32 v99, v123, v106
	v_fmac_f32_e32 v100, v124, v106
	v_fmac_f32_e32 v101, v125, v106
	ds_read_b128 v[118:121], v35 offset:41472
	ds_read_b128 v[122:125], v35 offset:41488
	s_waitcnt lgkmcnt(6)
	v_fmac_f32_e32 v94, v126, v107
	v_fmac_f32_e32 v95, v127, v107
	v_fmac_f32_e32 v96, v128, v107
	v_fmac_f32_e32 v97, v129, v107
	v_fmac_f32_e32 v98, v130, v107
	v_fmac_f32_e32 v99, v131, v107
	v_fmac_f32_e32 v100, v132, v107
	v_fmac_f32_e32 v101, v133, v107
	ds_read_b128 v[126:129], v35 offset:41728
	ds_read_b128 v[130:133], v35 offset:41744
	s_waitcnt lgkmcnt(6)
	v_fmac_f32_e32 v94, v134, v108
	v_fmac_f32_e32 v95, v135, v108
	v_fmac_f32_e32 v96, v136, v108
	v_fmac_f32_e32 v97, v137, v108
	v_fmac_f32_e32 v98, v138, v108
	v_fmac_f32_e32 v99, v139, v108
	v_fmac_f32_e32 v100, v140, v108
	v_fmac_f32_e32 v101, v141, v108
	ds_read_b128 v[134:137], v35 offset:41984
	ds_read_b128 v[138:141], v35 offset:42000
	s_waitcnt lgkmcnt(6)
	v_fmac_f32_e32 v94, v142, v109
	v_fmac_f32_e32 v95, v143, v109
	v_fmac_f32_e32 v96, v144, v109
	v_fmac_f32_e32 v97, v145, v109
	v_fmac_f32_e32 v98, v146, v109
	v_fmac_f32_e32 v99, v147, v109
	v_fmac_f32_e32 v100, v148, v109
	v_fmac_f32_e32 v101, v149, v109
	ds_read_b128 v[142:145], v35 offset:42240
	ds_read_b128 v[146:149], v35 offset:42256
	s_waitcnt lgkmcnt(6)
	v_fmac_f32_e32 v94, v118, v110
	v_fmac_f32_e32 v95, v119, v110
	v_fmac_f32_e32 v96, v120, v110
	v_fmac_f32_e32 v97, v121, v110
	v_fmac_f32_e32 v98, v122, v110
	v_fmac_f32_e32 v99, v123, v110
	v_fmac_f32_e32 v100, v124, v110
	v_fmac_f32_e32 v101, v125, v110
	ds_read_b128 v[118:121], v35 offset:42496
	ds_read_b128 v[122:125], v35 offset:42512
	s_waitcnt lgkmcnt(6)
	v_fmac_f32_e32 v94, v126, v111
	v_fmac_f32_e32 v95, v127, v111
	v_fmac_f32_e32 v96, v128, v111
	v_fmac_f32_e32 v97, v129, v111
	v_fmac_f32_e32 v98, v130, v111
	v_fmac_f32_e32 v99, v131, v111
	v_fmac_f32_e32 v100, v132, v111
	v_fmac_f32_e32 v101, v133, v111
	ds_read_b128 v[126:129], v35 offset:42752
	ds_read_b128 v[130:133], v35 offset:42768
	s_waitcnt lgkmcnt(6)
	v_fmac_f32_e32 v94, v134, v112
	v_fmac_f32_e32 v95, v135, v112
	v_fmac_f32_e32 v96, v136, v112
	v_fmac_f32_e32 v97, v137, v112
	v_fmac_f32_e32 v98, v138, v112
	v_fmac_f32_e32 v99, v139, v112
	v_fmac_f32_e32 v100, v140, v112
	v_fmac_f32_e32 v101, v141, v112
	ds_read_b128 v[134:137], v35 offset:43008
	ds_read_b128 v[138:141], v35 offset:43024
	s_waitcnt lgkmcnt(6)
	v_fmac_f32_e32 v94, v142, v113
	v_fmac_f32_e32 v95, v143, v113
	v_fmac_f32_e32 v96, v144, v113
	v_fmac_f32_e32 v97, v145, v113
	v_fmac_f32_e32 v98, v146, v113
	v_fmac_f32_e32 v99, v147, v113
	v_fmac_f32_e32 v100, v148, v113
	v_fmac_f32_e32 v101, v149, v113
	ds_read_b128 v[142:145], v35 offset:43264
	ds_read_b128 v[146:149], v35 offset:43280
	s_waitcnt lgkmcnt(6)
	v_fmac_f32_e32 v94, v118, v114
	v_fmac_f32_e32 v95, v119, v114
	v_fmac_f32_e32 v96, v120, v114
	v_fmac_f32_e32 v97, v121, v114
	v_fmac_f32_e32 v98, v122, v114
	v_fmac_f32_e32 v99, v123, v114
	v_fmac_f32_e32 v100, v124, v114
	v_fmac_f32_e32 v101, v125, v114
	s_waitcnt lgkmcnt(4)
	v_fmac_f32_e32 v94, v126, v115
	v_fmac_f32_e32 v95, v127, v115
	v_fmac_f32_e32 v96, v128, v115
	v_fmac_f32_e32 v97, v129, v115
	v_fmac_f32_e32 v98, v130, v115
	v_fmac_f32_e32 v99, v131, v115
	v_fmac_f32_e32 v100, v132, v115
	v_fmac_f32_e32 v101, v133, v115
	s_waitcnt lgkmcnt(2)
; DI float log_sigmoid_f(float z) { return fminf(z, 0.f) - __logf(1.0f + __expf(-fabsf(z))); }
; DI void gla_prep_item(const Args& A, int l, unsigned char* ldsb, int item, int tid, bool stage) {
;     ...
;     const u32x4* cp = (const u32x4*)(CODES + (tok0 + t) * 32);
;     const u32x4 cq0 = cp[0], cq1 = cp[1], cq2 = cp[2], cq3 = cp[3];
;     ...
;                 z[0] += cv * w0[0]; z[1] += cv * w0[1]; z[2] += cv * w0[2]; z[3] += cv * w0[3]; z[4] += cv * w1[0]; z[5] += cv * w1[1]; z[6] += cv * w1[2]; z[7] += cv * w1[3];
;             }
; #pragma unroll
;             for (int dd = 0; dd < 8; ++dd) gl[(dir * 64 + t) * 65 + 8 * dg + dd] = log_sigmoid_f(z[dd]) * (1.0f / 16.0f);
;         }
;     }
;     __syncthreads();
;     {
;         const int dir = tid >> 8, seg = (tid >> 6) & 3, d = tid & 63;
;         float* gp = gl + (dir * 64 + 16 * seg) * 65 + d; float v[16];
; #pragma unroll
;         for (int tt = 0; tt < 16; ++tt) v[tt] = gp[tt * 65];
;         if (dir == 0) {
; #pragma unroll
;             for (int tt = 1; tt < 16; ++tt) v[tt] += v[tt - 1];
;         } else {
; #pragma unroll
	v_fmac_f32_e32 v94, v134, v116
	v_fmac_f32_e32 v95, v135, v116
	v_fmac_f32_e32 v96, v136, v116
	v_fmac_f32_e32 v97, v137, v116
	v_fmac_f32_e32 v98, v138, v116
	v_fmac_f32_e32 v99, v139, v116
	v_fmac_f32_e32 v100, v140, v116
	v_fmac_f32_e32 v101, v141, v116
	s_waitcnt lgkmcnt(0)
	v_fmac_f32_e32 v94, v142, v117
	v_fmac_f32_e32 v95, v143, v117
	v_fmac_f32_e32 v96, v144, v117
	v_fmac_f32_e32 v97, v145, v117
	v_fmac_f32_e32 v98, v146, v117
	v_fmac_f32_e32 v99, v147, v117
	v_fmac_f32_e32 v100, v148, v117
	v_fmac_f32_e32 v101, v149, v117
	v_mul_f32_e64 v118, |v94|, s11
	v_mul_f32_e64 v119, |v95|, s11
	v_mul_f32_e64 v120, |v96|, s11
	v_mul_f32_e64 v121, |v97|, s11
	v_mul_f32_e64 v122, |v98|, s11
	v_mul_f32_e64 v123, |v99|, s11
	v_mul_f32_e64 v124, |v100|, s11
	v_mul_f32_e64 v125, |v101|, s11
	v_exp_f32_e32 v118, v118
	v_exp_f32_e32 v119, v119
	v_exp_f32_e32 v120, v120
	v_exp_f32_e32 v121, v121
	v_exp_f32_e32 v122, v122
	v_exp_f32_e32 v123, v123
	v_exp_f32_e32 v124, v124
	v_exp_f32_e32 v125, v125
	v_min_f32_e32 v142, 0, v94
	v_min_f32_e32 v143, 0, v95
	v_min_f32_e32 v144, 0, v96
	v_min_f32_e32 v145, 0, v97
	v_min_f32_e32 v146, 0, v98
	v_min_f32_e32 v147, 0, v99
	v_min_f32_e32 v148, 0, v100
	v_min_f32_e32 v149, 0, v101
	v_add_f32_e32 v118, 1.0, v118
	v_add_f32_e32 v119, 1.0, v119
	v_add_f32_e32 v120, 1.0, v120
	v_add_f32_e32 v121, 1.0, v121
	v_add_f32_e32 v122, 1.0, v122
	v_add_f32_e32 v123, 1.0, v123
	v_add_f32_e32 v124, 1.0, v124
	v_add_f32_e32 v125, 1.0, v125
	v_log_f32_e32 v126, v118
	v_log_f32_e32 v127, v119
	v_log_f32_e32 v128, v120
	v_log_f32_e32 v129, v121
	v_log_f32_e32 v130, v122
	v_log_f32_e32 v131, v123
	v_log_f32_e32 v132, v124
	v_log_f32_e32 v133, v125
	s_nop 0
	v_mul_f32_e32 v134, 0x3f317217, v126
	v_mul_f32_e32 v135, 0x3f317217, v127
	v_mul_f32_e32 v136, 0x3f317217, v128
	v_mul_f32_e32 v137, 0x3f317217, v129
	v_mul_f32_e32 v138, 0x3f317217, v130
	v_mul_f32_e32 v139, 0x3f317217, v131
	v_mul_f32_e32 v140, 0x3f317217, v132
	v_mul_f32_e32 v141, 0x3f317217, v133
	v_fma_f32 v134, v126, s81, -v134
	v_fma_f32 v135, v127, s81, -v135
	v_fma_f32 v136, v128, s81, -v136
	v_fma_f32 v137, v129, s81, -v137
	v_fma_f32 v138, v130, s81, -v138
	v_fma_f32 v139, v131, s81, -v139
	v_fma_f32 v140, v132, s81, -v140
	v_fma_f32 v141, v133, s81, -v141
	v_fmac_f32_e32 v134, 0x3377d1cf, v126
	v_fmac_f32_e32 v135, 0x3377d1cf, v127
	v_fmac_f32_e32 v136, 0x3377d1cf, v128
	v_fmac_f32_e32 v137, 0x3377d1cf, v129
	v_fmac_f32_e32 v138, 0x3377d1cf, v130
	v_fmac_f32_e32 v139, 0x3377d1cf, v131
	v_fmac_f32_e32 v140, 0x3377d1cf, v132
	v_fmac_f32_e32 v141, 0x3377d1cf, v133
	v_fmac_f32_e32 v134, 0x3f317217, v126
	v_fmac_f32_e32 v135, 0x3f317217, v127
	v_fmac_f32_e32 v136, 0x3f317217, v128
	v_fmac_f32_e32 v137, 0x3f317217, v129
	v_fmac_f32_e32 v138, 0x3f317217, v130
	v_fmac_f32_e32 v139, 0x3f317217, v131
	v_fmac_f32_e32 v140, 0x3f317217, v132
	v_fmac_f32_e32 v141, 0x3f317217, v133
	v_sub_f32_e32 v142, v142, v134
	v_sub_f32_e32 v143, v143, v135
	v_sub_f32_e32 v144, v144, v136
	v_sub_f32_e32 v145, v145, v137
	v_sub_f32_e32 v146, v146, v138
	v_sub_f32_e32 v147, v147, v139
	v_sub_f32_e32 v148, v148, v140
	v_sub_f32_e32 v149, v149, v141
	v_mul_f32_e32 v142, s18, v142
	v_mul_f32_e32 v143, s18, v143
	v_mul_f32_e32 v144, s18, v144
	v_mul_f32_e32 v145, s18, v145
	v_mul_f32_e32 v146, s18, v146
	v_mul_f32_e32 v147, s18, v147
	v_mul_f32_e32 v148, s18, v148
	v_mul_f32_e32 v149, s18, v149
	v_add_u32_e32 v47, 0x4100, v37
	v_add_u32_e32 v45, 0x4108, v37
	v_add_u32_e32 v43, 0x4110, v37
	v_add_u32_e32 v0, 0x4118, v37
	v_add_u32_e32 v52, 0x400, v32
	v_add_u32_e32 v51, 0x800, v32
	v_add_u32_e32 v50, 0xc00, v32
	ds_write2_b32 v47, v142, v143 offset1:1
	ds_write2_b32 v45, v144, v145 offset1:1
	ds_write2_b32 v43, v146, v147 offset1:1
	ds_write2_b32 v0, v148, v149 offset1:1
	s_waitcnt lgkmcnt(0)
	global_load_dwordx4 v[118:121], v[90:91], off
	global_load_dwordx4 v[122:125], v[90:91], off offset:48
	global_load_dwordx4 v[126:129], v[90:91], off offset:32
	global_load_dwordx4 v[130:133], v[90:91], off offset:16
	s_barrier
	ds_read2_b32 v[12:13], v32 offset1:65
	ds_read2_b32 v[14:15], v32 offset0:130 offset1:195
	ds_read2_b32 v[16:17], v52 offset0:4 offset1:69
	ds_read2_b32 v[18:19], v52 offset0:134 offset1:199
	ds_read2_b32 v[20:21], v51 offset0:8 offset1:73
	ds_read2_b32 v[22:23], v51 offset0:138 offset1:203
	ds_read2_b32 v[24:25], v50 offset0:12 offset1:77
	ds_read2_b32 v[10:11], v50 offset0:142 offset1:207
	s_and_saveexec_b64 s[2:3], s[42:43]
	s_xor_b64 s[2:3], exec, s[2:3]
	s_cbranch_execz .LBB0_574
	s_waitcnt lgkmcnt(0)
	v_add_f32_e32 v53, v10, v11
	v_add_f32_e32 v54, v25, v53
	v_add_f32_e32 v55, v24, v54
	v_add_f32_e32 v56, v23, v55
	v_add_f32_e32 v57, v22, v56
	v_add_f32_e32 v58, v21, v57
	v_add_f32_e32 v59, v20, v58
	v_add_f32_e32 v60, v19, v59
	v_add_f32_e32 v61, v18, v60
	v_add_f32_e32 v62, v17, v61
	v_add_f32_e32 v63, v16, v62
	v_add_f32_e32 v80, v15, v63
	v_add_f32_e32 v81, v14, v80
	v_add_f32_e32 v82, v13, v81
	v_add_f32_e32 v84, v12, v82
